# FFN-up epilogue: H stores write-through (sc1), drop per-wave buffer_wbl2 in ctx-unit publish
# speedup vs baseline: 1.0632x; 1.0632x over previous
.LBB0_85:
	v_mul_f32_e32 v152, 0xbfb8aa3b, v130
	v_exp_f32_e32 v152, v152
	v_lshl_or_b32 v144, s26, 7, v147
	v_readlane_b32 s26, v252, 5
	v_readlane_b32 s27, v252, 6
	v_add_f32_e32 v152, 1.0, v152
	v_rcp_f32_e32 v152, v152
	v_lshl_add_u32 v149, s50, 8, v37
	v_ashrrev_i32_e32 v145, 31, v144
	v_mov_b64_e32 v[142:143], s[26:27]
	v_mul_f32_e32 v130, v130, v152
	v_mul_f32_e32 v126, v130, v126
	v_mul_f32_e32 v130, 0xbfb8aa3b, v131
	v_exp_f32_e32 v130, v130
	s_movk_i32 s0, 0x1600
	v_mad_i64_i32 v[150:151], s[26:27], v149, s0, v[142:143]
	v_add_f32_e32 v130, 1.0, v130
	v_rcp_f32_e32 v130, v130
	v_lshlrev_b64 v[144:145], 1, v[144:145]
	v_lshl_add_u64 v[150:151], v[150:151], 0, v[144:145]
	s_cmp_lt_i32 s50, 64
	v_mul_f32_e32 v130, v131, v130
	v_mul_f32_e32 v127, v130, v127
	v_cvt_pk_bf16_f32 v126, v126, v127
	v_mul_f32_e32 v127, 0xbfb8aa3b, v132
	v_exp_f32_e32 v127, v127
	s_nop 0
	v_add_f32_e32 v127, 1.0, v127
	v_rcp_f32_e32 v127, v127
	s_nop 0
	v_mul_f32_e32 v127, v132, v127
	v_mul_f32_e32 v127, v127, v128
	v_mul_f32_e32 v128, 0xbfb8aa3b, v133
	v_exp_f32_e32 v128, v128
	s_nop 0
	v_add_f32_e32 v128, 1.0, v128
	v_rcp_f32_e32 v128, v128
	s_nop 0
	v_mul_f32_e32 v128, v133, v128
	v_mul_f32_e32 v128, v128, v129
	v_cvt_pk_bf16_f32 v127, v127, v128
	v_mul_f32_e32 v128, 0xbfb8aa3b, v122
	v_exp_f32_e32 v128, v128
	s_nop 0
	v_add_f32_e32 v128, 1.0, v128
	v_rcp_f32_e32 v128, v128
	s_nop 0
	v_mul_f32_e32 v122, v122, v128
	v_mul_f32_e32 v118, v122, v118
	v_mul_f32_e32 v122, 0xbfb8aa3b, v123
	v_exp_f32_e32 v122, v122
	s_nop 0
	v_add_f32_e32 v122, 1.0, v122
	v_rcp_f32_e32 v122, v122
	s_nop 0
	v_mul_f32_e32 v122, v123, v122
	v_mul_f32_e32 v119, v122, v119
	v_cvt_pk_bf16_f32 v128, v118, v119
	v_mul_f32_e32 v118, 0xbfb8aa3b, v124
	v_exp_f32_e32 v118, v118
	v_mul_f32_e32 v119, 0xbfb8aa3b, v125
	v_exp_f32_e32 v119, v119
	v_add_f32_e32 v118, 1.0, v118
	v_rcp_f32_e32 v118, v118
	v_add_f32_e32 v119, 1.0, v119
	v_rcp_f32_e32 v119, v119
	v_mul_f32_e32 v118, v124, v118
	v_mul_f32_e32 v118, v118, v120
	v_mul_f32_e32 v120, 0xbfb8aa3b, v114
	v_exp_f32_e32 v120, v120
	v_mul_f32_e32 v119, v125, v119
	v_mul_f32_e32 v119, v119, v121
	v_cvt_pk_bf16_f32 v129, v118, v119
	v_add_f32_e32 v120, 1.0, v120
	v_rcp_f32_e32 v120, v120
	global_store_dwordx4 v[150:151], v[126:129], off sc1
	v_or_b32_e32 v118, 16, v149
	v_mad_i64_i32 v[118:119], s[26:27], v118, s0, v[142:143]
	v_mul_f32_e32 v114, v114, v120
	v_mul_f32_e32 v110, v114, v110
	v_mul_f32_e32 v114, 0xbfb8aa3b, v115
	v_exp_f32_e32 v114, v114
	v_lshl_add_u64 v[118:119], v[118:119], 0, v[144:145]
	v_add_f32_e32 v114, 1.0, v114
	v_rcp_f32_e32 v114, v114
	s_nop 0
	v_mul_f32_e32 v114, v115, v114
	v_mul_f32_e32 v111, v114, v111
	v_cvt_pk_bf16_f32 v110, v110, v111
	v_mul_f32_e32 v111, 0xbfb8aa3b, v116
	v_exp_f32_e32 v111, v111
	s_nop 0
	v_add_f32_e32 v111, 1.0, v111
	v_rcp_f32_e32 v111, v111
	s_nop 0
	v_mul_f32_e32 v111, v116, v111
	v_mul_f32_e32 v111, v111, v112
	v_mul_f32_e32 v112, 0xbfb8aa3b, v117
	v_exp_f32_e32 v112, v112
	s_nop 0
	v_add_f32_e32 v112, 1.0, v112
	v_rcp_f32_e32 v112, v112
	s_nop 0
	v_mul_f32_e32 v112, v117, v112
	v_mul_f32_e32 v112, v112, v113
	v_cvt_pk_bf16_f32 v111, v111, v112
	v_mul_f32_e32 v112, 0xbfb8aa3b, v106
	v_exp_f32_e32 v112, v112
	s_nop 0
	v_add_f32_e32 v112, 1.0, v112
	v_rcp_f32_e32 v112, v112
	s_nop 0
	v_mul_f32_e32 v106, v106, v112
	v_mul_f32_e32 v102, v106, v102
	v_mul_f32_e32 v106, 0xbfb8aa3b, v107
	v_exp_f32_e32 v106, v106
	s_nop 0
	v_add_f32_e32 v106, 1.0, v106
	v_rcp_f32_e32 v106, v106
	s_nop 0
	v_mul_f32_e32 v106, v107, v106
	v_mul_f32_e32 v103, v106, v103
	v_cvt_pk_bf16_f32 v112, v102, v103
	v_mul_f32_e32 v102, 0xbfb8aa3b, v108
	v_exp_f32_e32 v102, v102
	v_mul_f32_e32 v103, 0xbfb8aa3b, v109
	v_exp_f32_e32 v103, v103
	v_add_f32_e32 v102, 1.0, v102
	v_rcp_f32_e32 v102, v102
	v_add_f32_e32 v103, 1.0, v103
	v_rcp_f32_e32 v103, v103
	v_mul_f32_e32 v102, v108, v102
	v_mul_f32_e32 v102, v102, v104
	v_mul_f32_e32 v104, 0xbfb8aa3b, v98
	v_exp_f32_e32 v104, v104
	v_mul_f32_e32 v103, v109, v103
	v_mul_f32_e32 v103, v103, v105
	v_cvt_pk_bf16_f32 v113, v102, v103
	v_add_f32_e32 v104, 1.0, v104
	v_rcp_f32_e32 v104, v104
	global_store_dwordx4 v[118:119], v[110:113], off sc1
	v_or_b32_e32 v102, 32, v149
	v_mad_i64_i32 v[102:103], s[26:27], v102, s0, v[142:143]
	v_mul_f32_e32 v98, v98, v104
	v_mul_f32_e32 v94, v98, v94
	v_mul_f32_e32 v98, 0xbfb8aa3b, v99
	v_exp_f32_e32 v98, v98
	v_lshl_add_u64 v[102:103], v[102:103], 0, v[144:145]
	v_add_f32_e32 v98, 1.0, v98
	v_rcp_f32_e32 v98, v98
	s_nop 0
	v_mul_f32_e32 v98, v99, v98
	v_mul_f32_e32 v95, v98, v95
	v_cvt_pk_bf16_f32 v94, v94, v95
	v_mul_f32_e32 v95, 0xbfb8aa3b, v100
	v_exp_f32_e32 v95, v95
	s_nop 0
	v_add_f32_e32 v95, 1.0, v95
	v_rcp_f32_e32 v95, v95
	s_nop 0
	v_mul_f32_e32 v95, v100, v95
	v_mul_f32_e32 v95, v95, v96
	v_mul_f32_e32 v96, 0xbfb8aa3b, v101
	v_exp_f32_e32 v96, v96
	s_nop 0
	v_add_f32_e32 v96, 1.0, v96
	v_rcp_f32_e32 v96, v96
	s_nop 0
	v_mul_f32_e32 v96, v101, v96
	v_mul_f32_e32 v96, v96, v97
	v_cvt_pk_bf16_f32 v95, v95, v96
	v_mul_f32_e32 v96, 0xbfb8aa3b, v90
	v_exp_f32_e32 v96, v96
	s_nop 0
	v_add_f32_e32 v96, 1.0, v96
	v_rcp_f32_e32 v96, v96
	s_nop 0
	v_mul_f32_e32 v90, v90, v96
	v_mul_f32_e32 v86, v90, v86
	v_mul_f32_e32 v90, 0xbfb8aa3b, v91
	v_exp_f32_e32 v90, v90
	s_nop 0
	v_add_f32_e32 v90, 1.0, v90
	v_rcp_f32_e32 v90, v90
	s_nop 0
	v_mul_f32_e32 v90, v91, v90
	v_mul_f32_e32 v87, v90, v87
	v_cvt_pk_bf16_f32 v96, v86, v87
	v_mul_f32_e32 v86, 0xbfb8aa3b, v92
	v_exp_f32_e32 v86, v86
	v_mul_f32_e32 v87, 0xbfb8aa3b, v93
	v_exp_f32_e32 v87, v87
	v_add_f32_e32 v86, 1.0, v86
	v_rcp_f32_e32 v86, v86
	v_add_f32_e32 v87, 1.0, v87
	v_rcp_f32_e32 v87, v87
	v_mul_f32_e32 v86, v92, v86
	v_mul_f32_e32 v86, v86, v88
	v_mul_f32_e32 v88, 0xbfb8aa3b, v82
	v_exp_f32_e32 v88, v88
	v_mul_f32_e32 v87, v93, v87
	v_mul_f32_e32 v87, v87, v89
	v_cvt_pk_bf16_f32 v97, v86, v87
	v_add_f32_e32 v88, 1.0, v88
	v_rcp_f32_e32 v88, v88
	global_store_dwordx4 v[102:103], v[94:97], off sc1
	v_or_b32_e32 v86, 48, v149
	v_mad_i64_i32 v[86:87], s[26:27], v86, s0, v[142:143]
	v_mul_f32_e32 v82, v82, v88
	v_mul_f32_e32 v78, v82, v78
	v_mul_f32_e32 v82, 0xbfb8aa3b, v83
	v_exp_f32_e32 v82, v82
	v_lshl_add_u64 v[86:87], v[86:87], 0, v[144:145]
	v_add_f32_e32 v82, 1.0, v82
	v_rcp_f32_e32 v82, v82
	s_nop 0
	v_mul_f32_e32 v82, v83, v82
	v_mul_f32_e32 v79, v82, v79
	v_cvt_pk_bf16_f32 v78, v78, v79
	v_mul_f32_e32 v79, 0xbfb8aa3b, v84
	v_exp_f32_e32 v79, v79
	s_nop 0
	v_add_f32_e32 v79, 1.0, v79
	v_rcp_f32_e32 v79, v79
	s_nop 0
	v_mul_f32_e32 v79, v84, v79
	v_mul_f32_e32 v79, v79, v80
	v_mul_f32_e32 v80, 0xbfb8aa3b, v85
	v_exp_f32_e32 v80, v80
	s_nop 0
	v_add_f32_e32 v80, 1.0, v80
	v_rcp_f32_e32 v80, v80
	s_nop 0
	v_mul_f32_e32 v80, v85, v80
	v_mul_f32_e32 v80, v80, v81
	v_cvt_pk_bf16_f32 v79, v79, v80
	v_mul_f32_e32 v80, 0xbfb8aa3b, v74
	v_exp_f32_e32 v80, v80
	s_nop 0
	v_add_f32_e32 v80, 1.0, v80
	v_rcp_f32_e32 v80, v80
	s_nop 0
	v_mul_f32_e32 v74, v74, v80
	v_mul_f32_e32 v70, v74, v70
	v_mul_f32_e32 v74, 0xbfb8aa3b, v75
	v_exp_f32_e32 v74, v74
	s_nop 0
	v_add_f32_e32 v74, 1.0, v74
	v_rcp_f32_e32 v74, v74
	s_nop 0
	v_mul_f32_e32 v74, v75, v74
	v_mul_f32_e32 v71, v74, v71
	v_cvt_pk_bf16_f32 v80, v70, v71
	v_mul_f32_e32 v70, 0xbfb8aa3b, v76
	v_exp_f32_e32 v70, v70
	v_mul_f32_e32 v71, 0xbfb8aa3b, v77
	v_exp_f32_e32 v71, v71
	v_add_f32_e32 v70, 1.0, v70
	v_rcp_f32_e32 v70, v70
	v_add_f32_e32 v71, 1.0, v71
	v_rcp_f32_e32 v71, v71
	v_mul_f32_e32 v70, v76, v70
	v_mul_f32_e32 v70, v70, v72
	v_mul_f32_e32 v72, 0xbfb8aa3b, v66
	v_exp_f32_e32 v72, v72
	v_mul_f32_e32 v71, v77, v71
	v_mul_f32_e32 v71, v71, v73
	v_cvt_pk_bf16_f32 v81, v70, v71
	v_add_f32_e32 v72, 1.0, v72
	v_rcp_f32_e32 v72, v72
	global_store_dwordx4 v[86:87], v[78:81], off sc1
	v_add_u32_e32 v70, 0x80, v149
	v_mad_i64_i32 v[70:71], s[26:27], v70, s0, v[142:143]
	v_mul_f32_e32 v66, v66, v72
	v_mul_f32_e32 v62, v66, v62
	v_mul_f32_e32 v66, 0xbfb8aa3b, v67
	v_exp_f32_e32 v66, v66
	v_lshl_add_u64 v[70:71], v[70:71], 0, v[144:145]
	v_add_f32_e32 v66, 1.0, v66
	v_rcp_f32_e32 v66, v66
	s_nop 0
	v_mul_f32_e32 v66, v67, v66
	v_mul_f32_e32 v63, v66, v63
	v_cvt_pk_bf16_f32 v62, v62, v63
	v_mul_f32_e32 v63, 0xbfb8aa3b, v68
	v_exp_f32_e32 v63, v63
	s_nop 0
	v_add_f32_e32 v63, 1.0, v63
	v_rcp_f32_e32 v63, v63
	s_nop 0
	v_mul_f32_e32 v63, v68, v63
	v_mul_f32_e32 v63, v63, v64
	v_mul_f32_e32 v64, 0xbfb8aa3b, v69
	v_exp_f32_e32 v64, v64
	s_nop 0
	v_add_f32_e32 v64, 1.0, v64
	v_rcp_f32_e32 v64, v64
	s_nop 0
	v_mul_f32_e32 v64, v69, v64
	v_mul_f32_e32 v64, v64, v65
	v_cvt_pk_bf16_f32 v63, v63, v64
	v_mul_f32_e32 v64, 0xbfb8aa3b, v58
	v_exp_f32_e32 v64, v64
	s_nop 0
	v_add_f32_e32 v64, 1.0, v64
	v_rcp_f32_e32 v64, v64
	s_nop 0
	v_mul_f32_e32 v58, v58, v64
	v_mul_f32_e32 v54, v58, v54
	v_mul_f32_e32 v58, 0xbfb8aa3b, v59
	v_exp_f32_e32 v58, v58
	s_nop 0
	v_add_f32_e32 v58, 1.0, v58
	v_rcp_f32_e32 v58, v58
	s_nop 0
	v_mul_f32_e32 v58, v59, v58
	v_mul_f32_e32 v55, v58, v55
	v_cvt_pk_bf16_f32 v64, v54, v55
	v_mul_f32_e32 v54, 0xbfb8aa3b, v60
	v_exp_f32_e32 v54, v54
	v_mul_f32_e32 v55, 0xbfb8aa3b, v61
	v_exp_f32_e32 v55, v55
	v_add_f32_e32 v54, 1.0, v54
	v_rcp_f32_e32 v54, v54
	v_add_f32_e32 v55, 1.0, v55
	v_rcp_f32_e32 v55, v55
	v_mul_f32_e32 v54, v60, v54
	v_mul_f32_e32 v54, v54, v56
	v_mul_f32_e32 v56, 0xbfb8aa3b, v50
	v_exp_f32_e32 v56, v56
	v_mul_f32_e32 v55, v61, v55
	v_mul_f32_e32 v55, v55, v57
	v_cvt_pk_bf16_f32 v65, v54, v55
	v_add_f32_e32 v56, 1.0, v56
	v_rcp_f32_e32 v56, v56
	global_store_dwordx4 v[70:71], v[62:65], off sc1
	v_add_u32_e32 v54, 0x90, v149
	v_mad_i64_i32 v[54:55], s[26:27], v54, s0, v[142:143]
	v_mul_f32_e32 v50, v50, v56
	v_mul_f32_e32 v46, v50, v46
	v_mul_f32_e32 v50, 0xbfb8aa3b, v51
	v_exp_f32_e32 v50, v50
	v_lshl_add_u64 v[54:55], v[54:55], 0, v[144:145]
	v_add_f32_e32 v50, 1.0, v50
	v_rcp_f32_e32 v50, v50
	s_nop 0
	v_mul_f32_e32 v50, v51, v50
	v_mul_f32_e32 v47, v50, v47
	v_cvt_pk_bf16_f32 v46, v46, v47
	v_mul_f32_e32 v47, 0xbfb8aa3b, v52
	v_exp_f32_e32 v47, v47
	s_nop 0
	v_add_f32_e32 v47, 1.0, v47
	v_rcp_f32_e32 v47, v47
	s_nop 0
	v_mul_f32_e32 v47, v52, v47
	v_mul_f32_e32 v47, v47, v48
	v_mul_f32_e32 v48, 0xbfb8aa3b, v53
	v_exp_f32_e32 v48, v48
	s_nop 0
	v_add_f32_e32 v48, 1.0, v48
	v_rcp_f32_e32 v48, v48
	s_nop 0
	v_mul_f32_e32 v48, v53, v48
	v_mul_f32_e32 v48, v48, v49
	v_cvt_pk_bf16_f32 v47, v47, v48
	v_mul_f32_e32 v48, 0xbfb8aa3b, v42
	v_exp_f32_e32 v48, v48
	s_nop 0
	v_add_f32_e32 v48, 1.0, v48
	v_rcp_f32_e32 v48, v48
	s_nop 0
	v_mul_f32_e32 v42, v42, v48
	v_mul_f32_e32 v38, v42, v38
	v_mul_f32_e32 v42, 0xbfb8aa3b, v43
	v_exp_f32_e32 v42, v42
	s_nop 0
	v_add_f32_e32 v42, 1.0, v42
	v_rcp_f32_e32 v42, v42
	s_nop 0
	v_mul_f32_e32 v42, v43, v42
	v_mul_f32_e32 v39, v42, v39
	v_cvt_pk_bf16_f32 v48, v38, v39
	v_mul_f32_e32 v38, 0xbfb8aa3b, v44
	v_exp_f32_e32 v38, v38
	v_mul_f32_e32 v39, 0xbfb8aa3b, v45
	v_exp_f32_e32 v39, v39
	v_add_f32_e32 v38, 1.0, v38
	v_rcp_f32_e32 v38, v38
	v_add_f32_e32 v39, 1.0, v39
	v_rcp_f32_e32 v39, v39
	v_mul_f32_e32 v38, v44, v38
	v_mul_f32_e32 v38, v38, v40
	v_mul_f32_e32 v40, 0xbfb8aa3b, v28
	v_exp_f32_e32 v40, v40
	v_mul_f32_e32 v39, v45, v39
	v_mul_f32_e32 v39, v39, v41
	v_cvt_pk_bf16_f32 v49, v38, v39
	v_add_f32_e32 v40, 1.0, v40
	v_rcp_f32_e32 v40, v40
	global_store_dwordx4 v[54:55], v[46:49], off sc1
	v_add_u32_e32 v38, 0xa0, v149
	v_mad_i64_i32 v[38:39], s[26:27], v38, s0, v[142:143]
	v_mul_f32_e32 v28, v28, v40
	v_mul_f32_e32 v24, v28, v24
	v_mul_f32_e32 v28, 0xbfb8aa3b, v29
	v_exp_f32_e32 v28, v28
	v_lshl_add_u64 v[38:39], v[38:39], 0, v[144:145]
	v_add_f32_e32 v28, 1.0, v28
	v_rcp_f32_e32 v28, v28
	s_nop 0
	v_mul_f32_e32 v28, v29, v28
	v_mul_f32_e32 v25, v28, v25
	v_cvt_pk_bf16_f32 v24, v24, v25
	v_mul_f32_e32 v25, 0xbfb8aa3b, v30
	v_exp_f32_e32 v25, v25
	s_nop 0
	v_add_f32_e32 v25, 1.0, v25
	v_rcp_f32_e32 v25, v25
	s_nop 0
	v_mul_f32_e32 v25, v30, v25
	v_mul_f32_e32 v25, v25, v26
	v_mul_f32_e32 v26, 0xbfb8aa3b, v31
	v_exp_f32_e32 v26, v26
	s_nop 0
	v_add_f32_e32 v26, 1.0, v26
	v_rcp_f32_e32 v26, v26
	s_nop 0
	v_mul_f32_e32 v26, v31, v26
	v_mul_f32_e32 v26, v26, v27
	v_cvt_pk_bf16_f32 v25, v25, v26
	v_mul_f32_e32 v26, 0xbfb8aa3b, v20
	v_exp_f32_e32 v26, v26
	s_nop 0
	v_add_f32_e32 v26, 1.0, v26
	v_rcp_f32_e32 v26, v26
	s_nop 0
	v_mul_f32_e32 v20, v20, v26
	v_mul_f32_e32 v16, v20, v16
	v_mul_f32_e32 v20, 0xbfb8aa3b, v21
	v_exp_f32_e32 v20, v20
	s_nop 0
	v_add_f32_e32 v20, 1.0, v20
	v_rcp_f32_e32 v20, v20
	s_nop 0
	v_mul_f32_e32 v20, v21, v20
	v_mul_f32_e32 v17, v20, v17
	v_cvt_pk_bf16_f32 v26, v16, v17
	v_mul_f32_e32 v16, 0xbfb8aa3b, v22
	v_exp_f32_e32 v16, v16
	v_mul_f32_e32 v17, 0xbfb8aa3b, v23
	v_exp_f32_e32 v17, v17
	v_add_f32_e32 v16, 1.0, v16
	v_rcp_f32_e32 v16, v16
	v_add_f32_e32 v17, 1.0, v17
	v_rcp_f32_e32 v17, v17
	v_mul_f32_e32 v16, v22, v16
	v_mul_f32_e32 v16, v16, v18
	v_mul_f32_e32 v18, 0xbfb8aa3b, v12
	v_exp_f32_e32 v18, v18
	v_mul_f32_e32 v17, v23, v17
	v_mul_f32_e32 v17, v17, v19
	v_cvt_pk_bf16_f32 v27, v16, v17
	v_add_f32_e32 v18, 1.0, v18
	v_rcp_f32_e32 v18, v18
	global_store_dwordx4 v[38:39], v[24:27], off sc1
	v_add_u32_e32 v16, 0xb0, v149
	v_mad_i64_i32 v[16:17], s[26:27], v16, s0, v[142:143]
	v_mul_f32_e32 v12, v12, v18
	v_mul_f32_e32 v8, v12, v8
	v_mul_f32_e32 v12, 0xbfb8aa3b, v13
	v_exp_f32_e32 v12, v12
	v_lshl_add_u64 v[16:17], v[16:17], 0, v[144:145]
	v_add_f32_e32 v12, 1.0, v12
	v_rcp_f32_e32 v12, v12
	s_nop 0
	v_mul_f32_e32 v12, v13, v12
	v_mul_f32_e32 v9, v12, v9
	v_cvt_pk_bf16_f32 v8, v8, v9
	v_mul_f32_e32 v9, 0xbfb8aa3b, v14
	v_exp_f32_e32 v9, v9
	s_nop 0
	v_add_f32_e32 v9, 1.0, v9
	v_rcp_f32_e32 v9, v9
	s_nop 0
	v_mul_f32_e32 v9, v14, v9
	v_mul_f32_e32 v9, v9, v10
	v_mul_f32_e32 v10, 0xbfb8aa3b, v15
	v_exp_f32_e32 v10, v10
	s_nop 0
	v_add_f32_e32 v10, 1.0, v10
	v_rcp_f32_e32 v10, v10
	s_nop 0
	v_mul_f32_e32 v10, v15, v10
	v_mul_f32_e32 v10, v10, v11
	v_cvt_pk_bf16_f32 v9, v9, v10
	v_mul_f32_e32 v10, 0xbfb8aa3b, v4
	v_exp_f32_e32 v10, v10
	s_nop 0
	v_add_f32_e32 v10, 1.0, v10
	v_rcp_f32_e32 v10, v10
	s_nop 0
	v_mul_f32_e32 v4, v4, v10
	v_mul_f32_e32 v0, v4, v0
	v_mul_f32_e32 v4, 0xbfb8aa3b, v5
	v_exp_f32_e32 v4, v4
	s_nop 0
	v_add_f32_e32 v4, 1.0, v4
	v_rcp_f32_e32 v4, v4
	s_nop 0
	v_mul_f32_e32 v4, v5, v4
	v_mul_f32_e32 v1, v4, v1
	v_cvt_pk_bf16_f32 v10, v0, v1
	v_mul_f32_e32 v0, 0xbfb8aa3b, v6
	v_mul_f32_e32 v1, 0xbfb8aa3b, v7
	v_exp_f32_e32 v0, v0
	v_exp_f32_e32 v1, v1
	v_add_f32_e32 v0, 1.0, v0
	v_add_f32_e32 v1, 1.0, v1
	v_rcp_f32_e32 v0, v0
	v_rcp_f32_e32 v1, v1
	v_mul_f32_e32 v0, v6, v0
	v_mul_f32_e32 v1, v7, v1
	v_mul_f32_e32 v0, v0, v2
	v_mul_f32_e32 v1, v1, v3
	v_cvt_pk_bf16_f32 v11, v0, v1
	global_store_dwordx4 v[16:17], v[8:11], off sc1
	s_cbranch_scc1 .LBB0_90
	s_waitcnt vmcnt(0)
	s_waitcnt vmcnt(0)
	s_waitcnt vmcnt(0)
	s_mov_b64 s[26:27], exec
	v_readlane_b32 s30, v254, 34
	v_readlane_b32 s31, v254, 35
	s_and_b64 s[30:31], s[26:27], s[30:31]
	s_mov_b64 exec, s[30:31]
	s_cbranch_execz .LBB0_89
	s_mov_b64 s[34:35], exec
	v_mbcnt_lo_u32_b32 v0, s34, 0
	v_mbcnt_hi_u32_b32 v0, s35, v0
	v_cmp_eq_u32_e32 vcc, 0, v0
	s_and_b64 s[30:31], exec, vcc
	s_mov_b64 exec, s[30:31]
	s_cbranch_execz .LBB0_89
	s_lshl_b32 s0, s50, 6
	s_lshl_b64 s[30:31], s[0:1], 2
	v_readlane_b32 s0, v255, 9
	s_add_u32 s0, s0, s30
	v_readlane_b32 s30, v255, 11
	s_addc_u32 s31, s30, s31
	s_add_u32 s30, s0, 0xffffc000
	s_addc_u32 s31, s31, -1
	s_bcnt1_i32_b64 s0, s[34:35]
	v_mov_b32_e32 v0, s0
	global_atomic_add v33, v0, s[30:31]
